# P1: per-ms modulation vectors summed once per workgroup (one (j,kind) vector per wave, shared through LDS) instead of redundantly by all 8 waves
# speedup vs baseline: 1.0121x; 1.0016x over previous
; __global__ void __launch_bounds__(512, 2) fwd_megakernel(Params Parg) {
;     ...
;         for (int ms = 0; ms < 3; ++ms) {
; #pragma unroll
;             for (int j = 0; j < 4; ++j) { const int c = 4 * lane + 256 * j;
;                 f32x4 sh = *(const f32x4*)(b_mod + c), sc = *(const f32x4*)(b_mod + D + c);
; #pragma unroll
;                 for (int p = 0; p < 8; ++p) { sh += *(const f32x4*)(part + (p * 3 + ms) * (NMOD * D) + c); sc += *(const f32x4*)(part + (p * 3 + ms) * (NMOD * D) + D + c); }
;                 shv[j] = sh; wv[j] = *(const f32x4*)(IN(6) + c) * (sc + 1.0f); }
.LBB0_227:
	s_mul_i32 s20, s4, 0x2400
	s_lshl_b64 s[6:7], s[20:21], 2
	s_add_u32 s6, s10, s6
	s_addc_u32 s7, s11, s7
	v_readfirstlane_b32 s26, v176
	s_lshr_b32 s26, s26, 6
	s_and_b32 s38, s26, 3
	s_lshr_b32 s34, s26, 2
	s_lshl_b32 s38, s38, 10
	s_lshl_b32 s34, s34, 12
	s_add_u32 s34, s34, s38
	s_mov_b32 s35, 0
	s_mov_b32 s39, 0
	v_add_u32_e32 v0, s34, v94
	v_lshl_add_u64 v[2:3], v[32:33], 0, s[34:35]
	v_lshl_add_u64 v[4:5], v[36:37], 0, s[38:39]
	global_load_dwordx4 v[8:11], v[2:3], off
	global_load_dwordx4 v[104:107], v0, s[6:7]
	s_add_u32 s6, s6, 0x1b000
	s_addc_u32 s7, s7, 0
	global_load_dwordx4 v[108:111], v0, s[6:7]
	s_add_u32 s6, s6, 0x1b000
	s_addc_u32 s7, s7, 0
	global_load_dwordx4 v[112:115], v0, s[6:7]
	s_add_u32 s6, s6, 0x1b000
	s_addc_u32 s7, s7, 0
	global_load_dwordx4 v[116:119], v0, s[6:7]
	s_add_u32 s6, s6, 0x1b000
	s_addc_u32 s7, s7, 0
	global_load_dwordx4 v[120:123], v0, s[6:7]
	s_add_u32 s6, s6, 0x1b000
	s_addc_u32 s7, s7, 0
	global_load_dwordx4 v[124:127], v0, s[6:7]
	s_add_u32 s6, s6, 0x1b000
	s_addc_u32 s7, s7, 0
	global_load_dwordx4 v[128:131], v0, s[6:7]
	s_add_u32 s6, s6, 0x1b000
	s_addc_u32 s7, s7, 0
	global_load_dwordx4 v[132:135], v0, s[6:7]
	global_load_dwordx4 v[100:103], v[4:5], off
	s_barrier
	s_waitcnt vmcnt(8)
	v_pk_add_f32 v[8:9], v[8:9], v[104:105]
	v_pk_add_f32 v[10:11], v[10:11], v[106:107]
	s_waitcnt vmcnt(7)
	v_pk_add_f32 v[8:9], v[8:9], v[108:109]
	v_pk_add_f32 v[10:11], v[10:11], v[110:111]
	s_waitcnt vmcnt(6)
	v_pk_add_f32 v[8:9], v[8:9], v[112:113]
	v_pk_add_f32 v[10:11], v[10:11], v[114:115]
	s_waitcnt vmcnt(5)
	v_pk_add_f32 v[8:9], v[8:9], v[116:117]
	v_pk_add_f32 v[10:11], v[10:11], v[118:119]
	s_waitcnt vmcnt(4)
	v_pk_add_f32 v[8:9], v[8:9], v[120:121]
	v_pk_add_f32 v[10:11], v[10:11], v[122:123]
	s_waitcnt vmcnt(3)
	v_pk_add_f32 v[8:9], v[8:9], v[124:125]
	v_pk_add_f32 v[10:11], v[10:11], v[126:127]
	s_waitcnt vmcnt(2)
	v_pk_add_f32 v[8:9], v[8:9], v[128:129]
	v_pk_add_f32 v[10:11], v[10:11], v[130:131]
	s_waitcnt vmcnt(1)
	v_pk_add_f32 v[8:9], v[8:9], v[132:133]
	v_pk_add_f32 v[10:11], v[10:11], v[134:135]
	s_waitcnt vmcnt(0)
	s_cmp_lt_u32 s26, 4
	s_cbranch_scc1 .Lp1_shift_vec
	v_pk_add_f32 v[8:9], v[8:9], 1.0 op_sel_hi:[1,0]
	v_pk_add_f32 v[10:11], v[10:11], 1.0 op_sel_hi:[1,0]
	v_pk_mul_f32 v[8:9], v[8:9], v[100:101]
	v_pk_mul_f32 v[10:11], v[10:11], v[102:103]
.Lp1_shift_vec:
	v_and_b32_e32 v6, 63, v176
	v_mul_u32_u24_e32 v6, 0x88, v6
	s_lshl_b32 s27, s26, 4
	v_add_u32_e32 v7, s27, v6
	ds_write2_b64 v7, v[8:9], v[10:11] offset1:1
	s_waitcnt lgkmcnt(0)
	s_barrier
	ds_read2_b64 v[52:55], v6 offset0:1 offset1:0
	ds_read2_b64 v[60:63], v6 offset0:3 offset1:2
	ds_read2_b64 v[68:71], v6 offset0:5 offset1:4
	ds_read2_b64 v[76:79], v6 offset0:7 offset1:6
	ds_read2_b64 v[56:59], v6 offset0:9 offset1:8
	ds_read2_b64 v[64:67], v6 offset0:11 offset1:10
	ds_read2_b64 v[72:75], v6 offset0:13 offset1:12
	ds_read2_b64 v[80:83], v6 offset0:15 offset1:14
	s_mov_b64 s[6:7], -1
	s_cmp_lg_u32 s4, 2
	s_waitcnt lgkmcnt(0)
	s_cbranch_scc0 .LBB0_231
	s_andn2_b64 vcc, exec, s[14:15]
	v_mov_b64_e32 v[84:85], v[48:49]
	v_mov_b64_e32 v[86:87], v[44:45]
	s_mov_b32 s5, s16
	s_cbranch_vccnz .LBB0_230
